# KMAX-AHEAD: attention unit prologue requests the key bound before the Q fragments instead of after their waits - one exposed round trip less per sample unit (on REL-FIRST)
# baseline (speedup 1.0000x reference)
.LBB0_985:
	s_and_b32 s42, s6, 7
	s_lshl_b32 s6, s26, 12
	s_and_b32 s27, s41, s40
	s_addk_i32 s6, 0x1000
	s_lshl_b32 s41, s26, 8
	s_and_b64 s[28:29], s[4:5], exec
	s_cselect_b32 s46, s6, s41
	s_lshr_b32 s45, s43, 2
	v_and_or_b32 v4, s45, 48, v152
	s_lshr_b32 s48, s43, 6
	v_lshl_add_u64 v[2:3], s[22:23], 0, v[130:131]
	s_lshl_b32 s6, s42, 8
	v_lshlrev_b32_e32 v4, 11, v4
	v_mov_b32_e32 v5, v131
	v_lshl_add_u64 v[2:3], v[2:3], 0, s[6:7]
	s_lshl_b32 s28, s48, 4
	s_mov_b32 s29, s7
	v_lshl_add_u64 v[4:5], s[24:25], 0, v[4:5]
	v_lshl_add_u64 v[2:3], v[2:3], 0, s[28:29]
	v_lshl_add_u64 v[4:5], v[4:5], 0, s[6:7]
	s_and_b32 s28, s45, 0x3fffffc0
	v_lshl_add_u64 v[4:5], v[4:5], 0, s[28:29]
	s_lshl_b32 s29, s48, 10
	v_mov_b32_e32 v139, v131
	s_add_i32 s48, s29, 0
	s_mov_b32 s49, m0
	s_mov_b32 m0, s48
	s_nop 0
	global_load_lds_dwordx4 v[2:3], off
	s_mov_b32 m0, s49
	v_lshl_add_u64 v[4:5], v[4:5], 0, v[138:139]
	v_lshl_add_u64 v[2:3], v[2:3], 0, s[16:17]
	s_add_i32 s49, s48, 0x2000
	s_mov_b32 s50, m0
	s_mov_b32 m0, s49
	s_nop 0
	global_load_lds_dwordx4 v[2:3], off
	s_mov_b32 m0, s50
	s_lshl_b32 s47, s27, 7
	s_lshr_b32 s27, s43, 7
	s_add_i32 s49, s48, 0xc000
	s_mov_b32 s50, m0
	s_mov_b32 m0, s49
	s_nop 0
	global_load_lds_dwordx4 v[4:5], off
	s_mov_b32 m0, s50
	v_lshl_add_u64 v[2:3], v[4:5], 0, s[16:17]
	s_add_i32 s48, s48, 0xe000
	s_mov_b32 s49, m0
	s_mov_b32 m0, s48
	s_nop 0
	global_load_lds_dwordx4 v[2:3], off
	s_mov_b32 m0, s49
	v_lshl_or_b32 v2, s27, 5, v151
	s_add_i32 s46, s46, s47
	v_add_u32_e32 v142, s46, v2
	v_ashrrev_i32_e32 v143, 31, v142
	v_lshlrev_b64 v[2:3], 11, v[142:143]
	s_bfe_u32 s41, s43, 0x10006
	v_lshl_add_u64 v[2:3], s[14:15], 0, v[2:3]
	v_lshl_add_u64 v[2:3], v[2:3], 0, s[6:7]
	s_lshl_b32 s46, s41, 7
	s_mov_b32 s47, s7
	v_lshl_add_u64 v[2:3], v[2:3], 0, s[46:47]
	v_mov_b32_e32 v141, v131
	v_lshl_add_u64 v[2:3], v[2:3], 0, v[140:141]
	s_andn2_b64 vcc, exec, s[4:5]
	s_cbranch_vccnz .Lkmax_skip
	s_lshl_b32 s76, s26, 4
	s_lshl_b32 s77, s42, 1
	s_or_b32 s76, s76, s77
	s_or_b32 s76, s76, s41
	s_ashr_i32 s77, s76, 31
	s_lshl_b64 s[76:77], s[76:77], 2
	s_add_u32 s76, s33, s76
	s_addc_u32 s77, s34, s77
	global_load_dword v252, v131, s[76:77]
.Lkmax_skip:
	global_load_dwordx4 v[126:129], v[2:3], off
	global_load_dwordx4 v[122:125], v[2:3], off offset:32
	global_load_dwordx4 v[118:121], v[2:3], off offset:64
	global_load_dwordx4 v[114:117], v[2:3], off offset:96
	s_andn2_b64 vcc, exec, s[4:5]
	s_waitcnt vmcnt(3)
	v_and_b32_e32 v2, 0xffff0000, v126
	v_lshlrev_b32_e32 v3, 16, v126
	v_mul_f32_e32 v2, v2, v2
	v_lshlrev_b32_e32 v4, 16, v127
	v_fmac_f32_e32 v2, v3, v3
	v_and_b32_e32 v5, 0xffff0000, v127
	v_fmac_f32_e32 v2, v4, v4
	v_lshlrev_b32_e32 v6, 16, v128
	v_fmac_f32_e32 v2, v5, v5
	v_and_b32_e32 v7, 0xffff0000, v128
	v_fmac_f32_e32 v2, v6, v6
	v_lshlrev_b32_e32 v8, 16, v129
	v_fmac_f32_e32 v2, v7, v7
	v_and_b32_e32 v9, 0xffff0000, v129
	v_fmac_f32_e32 v2, v8, v8
	s_waitcnt vmcnt(2)
	v_lshlrev_b32_e32 v10, 16, v122
	v_fmac_f32_e32 v2, v9, v9
	v_and_b32_e32 v11, 0xffff0000, v122
	v_fmac_f32_e32 v2, v10, v10
	v_lshlrev_b32_e32 v12, 16, v123
	v_fmac_f32_e32 v2, v11, v11
	v_and_b32_e32 v13, 0xffff0000, v123
	v_fmac_f32_e32 v2, v12, v12
	v_lshlrev_b32_e32 v14, 16, v124
	v_fmac_f32_e32 v2, v13, v13
	v_and_b32_e32 v15, 0xffff0000, v124
	v_fmac_f32_e32 v2, v14, v14
	v_lshlrev_b32_e32 v16, 16, v125
	v_fmac_f32_e32 v2, v15, v15
	v_and_b32_e32 v17, 0xffff0000, v125
	v_fmac_f32_e32 v2, v16, v16
	s_waitcnt vmcnt(1)
	v_lshlrev_b32_e32 v18, 16, v118
	v_fmac_f32_e32 v2, v17, v17
	v_and_b32_e32 v19, 0xffff0000, v118
	v_fmac_f32_e32 v2, v18, v18
	v_lshlrev_b32_e32 v20, 16, v119
	v_fmac_f32_e32 v2, v19, v19
	v_and_b32_e32 v21, 0xffff0000, v119
	v_fmac_f32_e32 v2, v20, v20
	v_lshlrev_b32_e32 v22, 16, v120
	v_fmac_f32_e32 v2, v21, v21
	v_and_b32_e32 v23, 0xffff0000, v120
	v_fmac_f32_e32 v2, v22, v22
	v_lshlrev_b32_e32 v24, 16, v121
	v_fmac_f32_e32 v2, v23, v23
	v_and_b32_e32 v25, 0xffff0000, v121
	v_fmac_f32_e32 v2, v24, v24
	s_waitcnt vmcnt(0)
	v_lshlrev_b32_e32 v26, 16, v114
	v_fmac_f32_e32 v2, v25, v25
	v_and_b32_e32 v27, 0xffff0000, v114
	v_fmac_f32_e32 v2, v26, v26
	v_lshlrev_b32_e32 v28, 16, v115
	v_fmac_f32_e32 v2, v27, v27
	v_and_b32_e32 v29, 0xffff0000, v115
	v_fmac_f32_e32 v2, v28, v28
	v_lshlrev_b32_e32 v30, 16, v116
	v_fmac_f32_e32 v2, v29, v29
	v_and_b32_e32 v31, 0xffff0000, v116
	v_fmac_f32_e32 v2, v30, v30
	v_lshlrev_b32_e32 v32, 16, v117
	v_fmac_f32_e32 v2, v31, v31
	v_fmac_f32_e32 v2, v32, v32
	v_and_b32_e32 v3, 0xffff0000, v117
	v_fmac_f32_e32 v2, v3, v3
	ds_bpermute_b32 v3, v1, v2
	v_mov_b32_e32 v4, v149
	s_cbranch_vccnz .LBB0_987
	s_lshl_b32 s4, s26, 4
	s_lshl_b32 s5, s42, 1
	s_or_b32 s4, s4, s5
	s_or_b32 s4, s4, s41
	s_ashr_i32 s5, s4, 31
	s_lshl_b64 s[4:5], s[4:5], 2
	s_add_u32 s4, s33, s4
	s_addc_u32 s5, s34, s5
	v_mov_b32_e32 v4, v252
	v_mul_f32_e32 v5, 0x4f800000, v4
	v_cmp_gt_f32_e32 vcc, s36, v4
	s_nop 1
	v_cndmask_b32_e32 v4, v4, v5, vcc
	v_sqrt_f32_e32 v5, v4
	s_nop 0
	v_add_u32_e32 v6, -1, v5
	v_add_u32_e32 v7, 1, v5
	v_fma_f32 v8, -v6, v5, v4
	v_fma_f32 v9, -v7, v5, v4
	v_cmp_ge_f32_e64 s[4:5], 0, v8
	s_nop 1
	v_cndmask_b32_e64 v5, v5, v6, s[4:5]
	v_cmp_lt_f32_e64 s[4:5], 0, v9
	s_nop 1
	v_cndmask_b32_e64 v5, v5, v7, s[4:5]
	v_mul_f32_e32 v6, 0x37800000, v5
	v_cndmask_b32_e32 v5, v5, v6, vcc
	v_cmp_class_f32_e32 vcc, v4, v156
	s_nop 1
	v_cndmask_b32_e32 v4, v5, v4, vcc
	v_mul_f32_e32 v4, 0x3f8147ae, v4
	v_max_f32_e32 v5, v149, v149
	v_max_f32_e32 v4, v5, v4
